# stack v138 with the split-barrier poll cap raised to 1M iterations (no other change)
# baseline (speedup 1.0000x reference)
.Lsw_poll:
	global_load_dword v251, v250, s[2:3] sc1
	s_waitcnt vmcnt(0)
	v_cmp_ne_u32_e32 vcc, s0, v251
	s_cbranch_vccnz .Lsw_got
	s_sleep 1
	s_add_i32 s1, s1, 1
	s_cmp_lt_u32 s1, 0x100000
	s_cbranch_scc1 .Lsw_poll
